# c3 without the deferred GEMM waits (baseline vmcnt(6) waits restored): EpiRes rolling epilogue, hmid stores without nt, XCD first barrier, batched forget-weight staging, attention wave priority
# baseline (speedup 1.0000x reference)
; template <class Epi, class Sched>
; __device__ __forceinline__ void gemm_phase(PG8_LAS unsigned char* lds, const Gemm g, const Sched& S, const Epi& E, int wv) {
;     ...
;     for (;;) {
;         const bool has_next = S.next(ui + 1, nxt);
;         const char* nA = has_next ? (const char*)g.A + (size_t)nxt.pm * tstepA : cA; const char* nB = has_next ? (const char*)g.Bt + (size_t)nxt.pn * tstep : cB;
;         int t0_ = 0;
;         if constexpr (Epi::HOIST) if (pre) { PG8_ITER_F(0); t0_ = 2; }
;         for (int t = t0_; t < nt; t += 2) { PG8_ITER_N(t); }
.LBB0_528:
	s_add_u32 s20, s81, s46
	s_addc_u32 s21, s82, 0
	s_add_u32 s83, s79, s46
	s_addc_u32 s84, s80, 0
	s_add_i32 s85, 0, 0x10000
	v_add_u32_e32 v0, s85, v147
	ds_read_b128 v[150:153], v0
	ds_read_b128 v[154:157], v0 offset:1024
	ds_read_b128 v[158:161], v0 offset:2048
	ds_read_b128 v[162:165], v0 offset:3072
	s_cmp_eq_u32 s46, s18
	s_cselect_b32 s23, s9, s21
	s_cselect_b32 s22, s76, s20
	s_cselect_b32 s21, s7, s84
	s_cselect_b32 s20, s77, s83
	s_add_i32 s84, s11, 0xc000
	v_lshl_add_u64 v[140:141], v[144:145], 0, s[46:47]
	s_mov_b32 m0, s84
	s_add_i32 s83, s11, 0xe000
	ds_read_b128 v[166:169], v149
	ds_read_b128 v[170:173], v149 offset:1024
	ds_read_b128 v[174:177], v149 offset:2048
	ds_read_b128 v[178:181], v149 offset:3072
	ds_read_b128 v[182:185], v149 offset:4096
	ds_read_b128 v[186:189], v149 offset:5120
	ds_read_b128 v[190:193], v149 offset:6144
	ds_read_b128 v[194:197], v149 offset:7168
	global_load_lds_dwordx4 v[140:141], off
	v_lshl_add_u64 v[140:141], v[2:3], 0, s[46:47]
	s_mov_b32 m0, s83
	s_nop 0
	global_load_lds_dwordx4 v[140:141], off
	s_waitcnt lgkmcnt(8)
	s_barrier
	s_waitcnt lgkmcnt(0)
	s_setprio 1
	s_waitcnt lgkmcnt(0)
	v_mfma_f32_16x16x32_bf16 v[124:127], v[150:153], v[166:169], v[124:127]
	v_mfma_f32_16x16x32_bf16 v[116:119], v[158:161], v[166:169], v[116:119]
	v_mfma_f32_16x16x32_bf16 v[108:111], v[150:153], v[174:177], v[108:111]
	v_mfma_f32_16x16x32_bf16 v[100:103], v[158:161], v[174:177], v[100:103]
	v_mfma_f32_16x16x32_bf16 v[92:95], v[150:153], v[182:185], v[92:95]
	v_mfma_f32_16x16x32_bf16 v[84:87], v[158:161], v[182:185], v[84:87]
	v_mfma_f32_16x16x32_bf16 v[76:79], v[150:153], v[190:193], v[76:79]
	v_mfma_f32_16x16x32_bf16 v[64:67], v[158:161], v[190:193], v[64:67]
	v_mfma_f32_16x16x32_bf16 v[124:127], v[154:157], v[170:173], v[124:127]
	v_mfma_f32_16x16x32_bf16 v[116:119], v[162:165], v[170:173], v[116:119]
	v_mfma_f32_16x16x32_bf16 v[108:111], v[154:157], v[178:181], v[108:111]
	v_mfma_f32_16x16x32_bf16 v[100:103], v[162:165], v[178:181], v[100:103]
	v_mfma_f32_16x16x32_bf16 v[92:95], v[154:157], v[186:189], v[92:95]
	v_mfma_f32_16x16x32_bf16 v[84:87], v[162:165], v[186:189], v[84:87]
	v_mfma_f32_16x16x32_bf16 v[76:79], v[154:157], v[194:197], v[76:79]
	v_mfma_f32_16x16x32_bf16 v[64:67], v[162:165], v[194:197], v[64:67]
	s_setprio 0
	s_barrier
	s_add_i32 s88, 0, 0x14000
	s_add_i32 s85, s85, s25
	v_add_u32_e32 v0, s88, v147
	v_lshl_add_u64 v[140:141], s[20:21], 0, v[136:137]
	s_mov_b32 m0, s85
	ds_read_b128 v[200:203], v0
	ds_read_b128 v[204:207], v0 offset:1024
	ds_read_b128 v[208:211], v0 offset:2048
	ds_read_b128 v[212:215], v0 offset:3072
	global_load_lds_dwordx4 v[140:141], off
	v_lshl_add_u64 v[142:143], s[20:21], 0, v[132:133]
	s_add_i32 m0, s85, 0x2000
	s_nop 0
	global_load_lds_dwordx4 v[142:143], off
	s_barrier
	s_waitcnt lgkmcnt(0)
	s_setprio 1
	s_waitcnt lgkmcnt(0)
	v_mfma_f32_16x16x32_bf16 v[128:131], v[200:203], v[166:169], v[128:131]
	v_mfma_f32_16x16x32_bf16 v[120:123], v[208:211], v[166:169], v[120:123]
	v_mfma_f32_16x16x32_bf16 v[112:115], v[200:203], v[174:177], v[112:115]
	v_mfma_f32_16x16x32_bf16 v[104:107], v[208:211], v[174:177], v[104:107]
	v_mfma_f32_16x16x32_bf16 v[96:99], v[200:203], v[182:185], v[96:99]
	v_mfma_f32_16x16x32_bf16 v[88:91], v[208:211], v[182:185], v[88:91]
	v_mfma_f32_16x16x32_bf16 v[80:83], v[200:203], v[190:193], v[80:83]
	v_mfma_f32_16x16x32_bf16 v[72:75], v[208:211], v[190:193], v[72:75]
	v_mfma_f32_16x16x32_bf16 v[128:131], v[204:207], v[170:173], v[128:131]
	v_mfma_f32_16x16x32_bf16 v[120:123], v[212:215], v[170:173], v[120:123]
	v_mfma_f32_16x16x32_bf16 v[112:115], v[204:207], v[178:181], v[112:115]
	v_mfma_f32_16x16x32_bf16 v[104:107], v[212:215], v[178:181], v[104:107]
	v_mfma_f32_16x16x32_bf16 v[96:99], v[204:207], v[186:189], v[96:99]
	v_mfma_f32_16x16x32_bf16 v[88:91], v[212:215], v[186:189], v[88:91]
	v_mfma_f32_16x16x32_bf16 v[80:83], v[204:207], v[194:197], v[80:83]
	v_mfma_f32_16x16x32_bf16 v[72:75], v[212:215], v[194:197], v[72:75]
	s_setprio 0
	s_mov_b32 m0, s11
	v_lshl_add_u64 v[198:199], s[22:23], 0, v[138:139]
	s_barrier
	ds_read_b128 v[166:169], v149 offset:16384
	ds_read_b128 v[170:173], v149 offset:17408
	ds_read_b128 v[174:177], v149 offset:18432
	ds_read_b128 v[178:181], v149 offset:19456
	ds_read_b128 v[182:185], v149 offset:20480
	ds_read_b128 v[186:189], v149 offset:21504
	ds_read_b128 v[190:193], v149 offset:22528
	ds_read_b128 v[194:197], v149 offset:23552
	global_load_lds_dwordx4 v[198:199], off
	v_lshl_add_u64 v[218:219], s[22:23], 0, v[134:135]
	s_mov_b32 m0, s57
	s_nop 0
	global_load_lds_dwordx4 v[218:219], off
	s_barrier
	s_waitcnt lgkmcnt(0)
	s_setprio 1
	s_waitcnt lgkmcnt(0)
	v_mfma_f32_16x16x32_bf16 v[60:63], v[150:153], v[166:169], v[60:63]
	v_mfma_f32_16x16x32_bf16 v[52:55], v[158:161], v[166:169], v[52:55]
	v_mfma_f32_16x16x32_bf16 v[44:47], v[150:153], v[174:177], v[44:47]
	v_mfma_f32_16x16x32_bf16 v[36:39], v[158:161], v[174:177], v[36:39]
	v_mfma_f32_16x16x32_bf16 v[28:31], v[150:153], v[182:185], v[28:31]
	v_mfma_f32_16x16x32_bf16 v[20:23], v[158:161], v[182:185], v[20:23]
	v_mfma_f32_16x16x32_bf16 v[12:15], v[150:153], v[190:193], v[12:15]
	v_mfma_f32_16x16x32_bf16 v[4:7], v[158:161], v[190:193], v[4:7]
	v_mfma_f32_16x16x32_bf16 v[60:63], v[154:157], v[170:173], v[60:63]
	v_mfma_f32_16x16x32_bf16 v[52:55], v[162:165], v[170:173], v[52:55]
	v_mfma_f32_16x16x32_bf16 v[44:47], v[154:157], v[178:181], v[44:47]
	v_mfma_f32_16x16x32_bf16 v[36:39], v[162:165], v[178:181], v[36:39]
	v_mfma_f32_16x16x32_bf16 v[28:31], v[154:157], v[186:189], v[28:31]
	v_mfma_f32_16x16x32_bf16 v[20:23], v[162:165], v[186:189], v[20:23]
	v_mfma_f32_16x16x32_bf16 v[12:15], v[154:157], v[194:197], v[12:15]
	v_mfma_f32_16x16x32_bf16 v[4:7], v[162:165], v[194:197], v[4:7]
	s_setprio 0
	s_barrier
	s_add_u32 s86, s20, 0x40000
	s_addc_u32 s87, s21, 0
	s_add_i32 s85, s88, s25
	v_lshl_add_u64 v[150:151], s[86:87], 0, v[136:137]
	s_mov_b32 m0, s85
	s_nop 0
	global_load_lds_dwordx4 v[150:151], off
	v_lshl_add_u64 v[150:151], s[86:87], 0, v[132:133]
	s_add_i32 m0, s85, 0x2000
	s_nop 0
	global_load_lds_dwordx4 v[150:151], off
	s_waitcnt vmcnt(6)
	s_barrier
	s_setprio 1
	v_mfma_f32_16x16x32_bf16 v[68:71], v[200:203], v[166:169], v[68:71]
	v_mfma_f32_16x16x32_bf16 v[56:59], v[208:211], v[166:169], v[56:59]
	v_mfma_f32_16x16x32_bf16 v[48:51], v[200:203], v[174:177], v[48:51]
	v_mfma_f32_16x16x32_bf16 v[40:43], v[208:211], v[174:177], v[40:43]
	v_mfma_f32_16x16x32_bf16 v[32:35], v[200:203], v[182:185], v[32:35]
	v_mfma_f32_16x16x32_bf16 v[24:27], v[208:211], v[182:185], v[24:27]
	v_mfma_f32_16x16x32_bf16 v[16:19], v[200:203], v[190:193], v[16:19]
	v_mfma_f32_16x16x32_bf16 v[8:11], v[208:211], v[190:193], v[8:11]
	v_mfma_f32_16x16x32_bf16 v[68:71], v[204:207], v[170:173], v[68:71]
	v_mfma_f32_16x16x32_bf16 v[56:59], v[212:215], v[170:173], v[56:59]
	v_mfma_f32_16x16x32_bf16 v[48:51], v[204:207], v[178:181], v[48:51]
	v_mfma_f32_16x16x32_bf16 v[40:43], v[212:215], v[178:181], v[40:43]
	v_mfma_f32_16x16x32_bf16 v[32:35], v[204:207], v[186:189], v[32:35]
	v_mfma_f32_16x16x32_bf16 v[24:27], v[212:215], v[186:189], v[24:27]
	v_mfma_f32_16x16x32_bf16 v[16:19], v[204:207], v[194:197], v[16:19]
	v_mfma_f32_16x16x32_bf16 v[8:11], v[212:215], v[194:197], v[8:11]
	s_setprio 0
	s_add_i32 s85, 0, 0x18000
	v_add_u32_e32 v0, s85, v147
	s_barrier
	ds_read_b128 v[150:153], v0
	ds_read_b128 v[154:157], v0 offset:1024
	ds_read_b128 v[158:161], v0 offset:2048
	ds_read_b128 v[162:165], v0 offset:3072
	s_add_u32 s22, s22, 0x40000
	s_addc_u32 s23, s23, 0
	s_mov_b32 m0, s58
	v_lshl_add_u64 v[200:201], s[22:23], 0, v[138:139]
	ds_read_b128 v[166:169], v149 offset:32768
	ds_read_b128 v[170:173], v149 offset:33792
	ds_read_b128 v[174:177], v149 offset:34816
	ds_read_b128 v[178:181], v149 offset:35840
	ds_read_b128 v[182:185], v149 offset:36864
	ds_read_b128 v[186:189], v149 offset:37888
	ds_read_b128 v[190:193], v149 offset:38912
	ds_read_b128 v[194:197], v149 offset:39936
	global_load_lds_dwordx4 v[200:201], off
	v_lshl_add_u64 v[200:201], s[22:23], 0, v[134:135]
	s_mov_b32 m0, s59
	s_nop 0
	global_load_lds_dwordx4 v[200:201], off
	s_waitcnt lgkmcnt(8)
	s_barrier
	s_waitcnt lgkmcnt(0)
	s_setprio 1
	s_waitcnt lgkmcnt(0)
	v_mfma_f32_16x16x32_bf16 v[124:127], v[150:153], v[166:169], v[124:127]
	v_mfma_f32_16x16x32_bf16 v[116:119], v[158:161], v[166:169], v[116:119]
	v_mfma_f32_16x16x32_bf16 v[108:111], v[150:153], v[174:177], v[108:111]
	v_mfma_f32_16x16x32_bf16 v[100:103], v[158:161], v[174:177], v[100:103]
	v_mfma_f32_16x16x32_bf16 v[92:95], v[150:153], v[182:185], v[92:95]
	v_mfma_f32_16x16x32_bf16 v[84:87], v[158:161], v[182:185], v[84:87]
	v_mfma_f32_16x16x32_bf16 v[76:79], v[150:153], v[190:193], v[76:79]
	v_mfma_f32_16x16x32_bf16 v[64:67], v[158:161], v[190:193], v[64:67]
	v_mfma_f32_16x16x32_bf16 v[124:127], v[154:157], v[170:173], v[124:127]
	v_mfma_f32_16x16x32_bf16 v[116:119], v[162:165], v[170:173], v[116:119]
	v_mfma_f32_16x16x32_bf16 v[108:111], v[154:157], v[178:181], v[108:111]
	v_mfma_f32_16x16x32_bf16 v[100:103], v[162:165], v[178:181], v[100:103]
	v_mfma_f32_16x16x32_bf16 v[92:95], v[154:157], v[186:189], v[92:95]
	v_mfma_f32_16x16x32_bf16 v[84:87], v[162:165], v[186:189], v[84:87]
	v_mfma_f32_16x16x32_bf16 v[76:79], v[154:157], v[194:197], v[76:79]
	v_mfma_f32_16x16x32_bf16 v[64:67], v[162:165], v[194:197], v[64:67]
	s_setprio 0
	s_barrier
	s_add_i32 s22, 0, 0x1c000
	s_add_i32 s23, s85, s25
	v_add_u32_e32 v0, s22, v147
	v_lshl_add_u64 v[140:141], v[140:141], 0, s[48:49]
	s_mov_b32 m0, s23
	ds_read_b128 v[200:203], v0
	ds_read_b128 v[204:207], v0 offset:1024
	ds_read_b128 v[208:211], v0 offset:2048
	ds_read_b128 v[212:215], v0 offset:3072
	global_load_lds_dwordx4 v[140:141], off
	v_lshl_add_u64 v[140:141], v[142:143], 0, s[48:49]
	s_add_i32 m0, s23, 0x2000
	s_nop 0
	global_load_lds_dwordx4 v[140:141], off
	s_barrier
	s_waitcnt lgkmcnt(0)
	s_setprio 1
	s_waitcnt lgkmcnt(0)
	v_mfma_f32_16x16x32_bf16 v[128:131], v[200:203], v[166:169], v[128:131]
	v_mfma_f32_16x16x32_bf16 v[120:123], v[208:211], v[166:169], v[120:123]
	v_mfma_f32_16x16x32_bf16 v[112:115], v[200:203], v[174:177], v[112:115]
	v_mfma_f32_16x16x32_bf16 v[104:107], v[208:211], v[174:177], v[104:107]
	v_mfma_f32_16x16x32_bf16 v[96:99], v[200:203], v[182:185], v[96:99]
	v_mfma_f32_16x16x32_bf16 v[88:91], v[208:211], v[182:185], v[88:91]
	v_mfma_f32_16x16x32_bf16 v[80:83], v[200:203], v[190:193], v[80:83]
	v_mfma_f32_16x16x32_bf16 v[72:75], v[208:211], v[190:193], v[72:75]
	v_mfma_f32_16x16x32_bf16 v[128:131], v[204:207], v[170:173], v[128:131]
	v_mfma_f32_16x16x32_bf16 v[120:123], v[212:215], v[170:173], v[120:123]
	v_mfma_f32_16x16x32_bf16 v[112:115], v[204:207], v[178:181], v[112:115]
	v_mfma_f32_16x16x32_bf16 v[104:107], v[212:215], v[178:181], v[104:107]
	v_mfma_f32_16x16x32_bf16 v[96:99], v[204:207], v[186:189], v[96:99]
	v_mfma_f32_16x16x32_bf16 v[88:91], v[212:215], v[186:189], v[88:91]
	v_mfma_f32_16x16x32_bf16 v[80:83], v[204:207], v[194:197], v[80:83]
	v_mfma_f32_16x16x32_bf16 v[72:75], v[212:215], v[194:197], v[72:75]
	s_setprio 0
	s_mov_b32 m0, s60
	v_lshl_add_u64 v[140:141], v[198:199], 0, s[48:49]
	s_barrier
	ds_read_b128 v[166:169], v149 offset:49152
	ds_read_b128 v[170:173], v149 offset:50176
	ds_read_b128 v[174:177], v149 offset:51200
	ds_read_b128 v[178:181], v149 offset:52224
	ds_read_b128 v[182:185], v149 offset:53248
	ds_read_b128 v[186:189], v149 offset:54272
	ds_read_b128 v[190:193], v149 offset:55296
	ds_read_b128 v[194:197], v149 offset:56320
	global_load_lds_dwordx4 v[140:141], off
	v_lshl_add_u64 v[140:141], v[218:219], 0, s[48:49]
	s_mov_b32 m0, s61
	s_nop 0
	global_load_lds_dwordx4 v[140:141], off
	s_barrier
; DEVI unsigned cvtpk(float lo, float hi) { unsigned r; asm volatile("v_cvt_pk_bf16_f32 %0, %1, %2" : "=v"(r) : "v"(lo), "v"(hi)); return r; }
; DEVI float sigmoidf_(float x) { return __builtin_amdgcn_rcpf(1.f + __expf(-x)); }
;     DEVI void operator()(AccRef acc, const pg8::Unit& u, int wr, int wc, int fr, int fq) const {
;         const int row0 = u.pm * 256 + wr * 64 + fr, col = u.pn * 128 + wc * 32 + 8 * fq;
; #pragma unroll
;         for (int ai = 0; ai < 2; ++ai)
; #pragma unroll
;             for (int m = 0; m < 4; ++m) { bf16_t* rowp = Hm + (size_t)(row0 + ai * 128 + m * 16) * DFF + col; float h[8];
; #pragma unroll
;                 for (int j = 0; j < 8; ++j) { const float gt = acc[ai][0][m][j >> 2][j & 3], up = acc[ai][1][m][j >> 2][j & 3]; h[j] = gt * sigmoidf_(gt) * up; }
;                 u32x4 w; w.x = cvtpk(h[0], h[1]); w.y = cvtpk(h[2], h[3]); w.z = cvtpk(h[4], h[5]); w.w = cvtpk(h[6], h[7]);
;                 if (ai == 0 && m == 0) asm volatile("s_waitcnt vmcnt(0)" ::: "memory");
	s_waitcnt lgkmcnt(0)
	s_setprio 1
	s_waitcnt lgkmcnt(0)
	v_mfma_f32_16x16x32_bf16 v[60:63], v[150:153], v[166:169], v[60:63]
	v_mfma_f32_16x16x32_bf16 v[52:55], v[158:161], v[166:169], v[52:55]
	v_mfma_f32_16x16x32_bf16 v[44:47], v[150:153], v[174:177], v[44:47]
	v_mfma_f32_16x16x32_bf16 v[36:39], v[158:161], v[174:177], v[36:39]
	v_mfma_f32_16x16x32_bf16 v[28:31], v[150:153], v[182:185], v[28:31]
	v_mfma_f32_16x16x32_bf16 v[20:23], v[158:161], v[182:185], v[20:23]
	v_mfma_f32_16x16x32_bf16 v[12:15], v[150:153], v[190:193], v[12:15]
	v_mfma_f32_16x16x32_bf16 v[4:7], v[158:161], v[190:193], v[4:7]
	v_mfma_f32_16x16x32_bf16 v[60:63], v[154:157], v[170:173], v[60:63]
	v_mfma_f32_16x16x32_bf16 v[52:55], v[162:165], v[170:173], v[52:55]
	v_mfma_f32_16x16x32_bf16 v[44:47], v[154:157], v[178:181], v[44:47]
	v_mfma_f32_16x16x32_bf16 v[36:39], v[162:165], v[178:181], v[36:39]
	v_mfma_f32_16x16x32_bf16 v[28:31], v[154:157], v[186:189], v[28:31]
	v_mfma_f32_16x16x32_bf16 v[20:23], v[162:165], v[186:189], v[20:23]
	v_mfma_f32_16x16x32_bf16 v[12:15], v[154:157], v[194:197], v[12:15]
	v_mfma_f32_16x16x32_bf16 v[4:7], v[162:165], v[194:197], v[4:7]
	s_setprio 0
	s_barrier
	s_add_u32 s20, s20, 0x40080
	s_addc_u32 s21, s21, 0
	s_add_i32 s22, s22, s25
	v_lshl_add_u64 v[140:141], s[20:21], 0, v[136:137]
	s_mov_b32 m0, s22
	s_nop 0
	global_load_lds_dwordx4 v[140:141], off
	v_lshl_add_u64 v[140:141], s[20:21], 0, v[132:133]
	s_add_i32 m0, s22, 0x2000
	s_nop 0
	global_load_lds_dwordx4 v[140:141], off
	s_waitcnt vmcnt(6)
	s_barrier
	s_setprio 1
	v_mfma_f32_16x16x32_bf16 v[68:71], v[200:203], v[166:169], v[68:71]
	v_mfma_f32_16x16x32_bf16 v[56:59], v[208:211], v[166:169], v[56:59]
	v_mfma_f32_16x16x32_bf16 v[48:51], v[200:203], v[174:177], v[48:51]
	v_mfma_f32_16x16x32_bf16 v[40:43], v[208:211], v[174:177], v[40:43]
	v_mfma_f32_16x16x32_bf16 v[32:35], v[200:203], v[182:185], v[32:35]
	v_mfma_f32_16x16x32_bf16 v[24:27], v[208:211], v[182:185], v[24:27]
	v_mfma_f32_16x16x32_bf16 v[16:19], v[200:203], v[190:193], v[16:19]
	v_mfma_f32_16x16x32_bf16 v[8:11], v[208:211], v[190:193], v[8:11]
	v_mfma_f32_16x16x32_bf16 v[68:71], v[204:207], v[170:173], v[68:71]
	v_mfma_f32_16x16x32_bf16 v[56:59], v[212:215], v[170:173], v[56:59]
	v_mfma_f32_16x16x32_bf16 v[48:51], v[204:207], v[178:181], v[48:51]
	v_mfma_f32_16x16x32_bf16 v[40:43], v[212:215], v[178:181], v[40:43]
	v_mfma_f32_16x16x32_bf16 v[32:35], v[204:207], v[186:189], v[32:35]
	v_mfma_f32_16x16x32_bf16 v[24:27], v[212:215], v[186:189], v[24:27]
	v_mfma_f32_16x16x32_bf16 v[16:19], v[204:207], v[194:197], v[16:19]
	v_mfma_f32_16x16x32_bf16 v[8:11], v[212:215], v[194:197], v[8:11]
	s_setprio 0
	s_add_i32 s78, s78, 2
	s_add_u32 s79, s79, 0x100
	s_addc_u32 s80, s80, 0
	s_add_u32 s81, s81, 0x100
	s_addc_u32 s82, s82, 0
	s_add_u32 s18, s18, 0xffffff00
	s_addc_u32 s19, s19, -1
	v_lshl_add_u64 v[2:3], v[2:3], 0, s[50:51]
	s_cmp_gt_u32 s78, 13
	v_lshl_add_u64 v[144:145], v[144:145], 0, s[50:51]
	s_barrier
	s_cbranch_scc0 .LBB0_528
	s_add_u32 s18, s76, 0x40080
	s_addc_u32 s19, s9, 0
	s_mov_b32 m0, s84
	v_lshl_add_u64 v[2:3], s[18:19], 0, v[138:139]
	global_load_lds_dwordx4 v[2:3], off
	v_lshl_add_u64 v[2:3], s[18:19], 0, v[134:135]
	s_mov_b32 m0, s83
	v_lshl_or_b32 v140, s75, 7, v148
	global_load_lds_dwordx4 v[2:3], off
	v_mul_f32_e32 v2, 0xbfb8aa3b, v124
	v_exp_f32_e32 v142, v2
	v_mul_f32_e32 v2, 0xbfb8aa3b, v125
	v_exp_f32_e32 v143, v2
	v_lshl_add_u32 v0, s10, 8, v146
	v_add_f32_e32 v142, 1.0, v142
	v_rcp_f32_e32 v144, v142
	v_add_f32_e32 v142, 1.0, v143
	v_rcp_f32_e32 v145, v142
	v_ashrrev_i32_e32 v141, 31, v140
	v_mul_f32_e32 v124, v124, v144
	v_mul_f32_e32 v124, v124, v128
	v_mul_f32_e32 v128, 0xbfb8aa3b, v126
	v_mul_f32_e32 v144, 0xbfb8aa3b, v127
	v_exp_f32_e32 v128, v128
	v_exp_f32_e32 v144, v144
	v_mul_f32_e32 v125, v125, v145
	v_mul_f32_e32 v125, v125, v129
	v_add_f32_e32 v128, 1.0, v128
	v_add_f32_e32 v129, 1.0, v144
	v_mul_f32_e32 v144, 0xbfb8aa3b, v116
	v_rcp_f32_e32 v128, v128
	v_exp_f32_e32 v144, v144
	v_rcp_f32_e32 v129, v129
	v_mov_b64_e32 v[2:3], s[68:69]
	v_mul_f32_e32 v126, v126, v128
	v_add_f32_e32 v128, 1.0, v144
	v_mul_f32_e32 v127, v127, v129
	v_rcp_f32_e32 v128, v128
	v_mul_f32_e32 v129, 0xbfb8aa3b, v117
	v_exp_f32_e32 v129, v129
	v_mad_i64_i32 v[142:143], s[18:19], v0, s3, v[2:3]
	v_mul_f32_e32 v116, v116, v128
	v_mul_f32_e32 v120, v116, v120
	v_add_f32_e32 v116, 1.0, v129
	v_mul_f32_e32 v128, 0xbfb8aa3b, v118
	v_rcp_f32_e32 v116, v116
	v_exp_f32_e32 v128, v128
	v_mul_f32_e32 v129, 0xbfb8aa3b, v119
	v_exp_f32_e32 v129, v129
	v_mul_f32_e32 v116, v117, v116
	v_add_f32_e32 v117, 1.0, v128
	v_rcp_f32_e32 v117, v117
	v_mul_f32_e32 v121, v116, v121
	v_add_f32_e32 v128, 1.0, v129
	v_rcp_f32_e32 v128, v128
	v_mul_f32_e32 v116, v118, v117
	v_cvt_pk_bf16_f32 v118, v124, v125
	v_mul_f32_e32 v124, 0xbfb8aa3b, v108
	v_exp_f32_e32 v124, v124
	v_mul_f32_e32 v125, 0xbfb8aa3b, v109
	v_exp_f32_e32 v125, v125
	v_mul_f32_e32 v129, v116, v122
	v_add_f32_e32 v124, 1.0, v124
	v_rcp_f32_e32 v124, v124
	v_mul_f32_e32 v116, v119, v128
	v_mul_f32_e32 v128, v116, v123
	v_lshlrev_b64 v[116:117], 1, v[140:141]
	v_lshl_add_u64 v[122:123], v[142:143], 0, v[116:117]
	v_add_f32_e32 v125, 1.0, v125
	v_mul_f32_e32 v108, v108, v124
	v_mul_f32_e32 v126, v126, v130
	v_mul_f32_e32 v127, v127, v131
	v_cvt_pk_bf16_f32 v119, v126, v127
	v_cvt_pk_bf16_f32 v120, v120, v121
	v_cvt_pk_bf16_f32 v121, v129, v128
	s_waitcnt vmcnt(0)
; DEVI unsigned cvtpk(float lo, float hi) { unsigned r; asm volatile("v_cvt_pk_bf16_f32 %0, %1, %2" : "=v"(r) : "v"(lo), "v"(hi)); return r; }
; DEVI float sigmoidf_(float x) { return __builtin_amdgcn_rcpf(1.f + __expf(-x)); }
;     DEVI void operator()(AccRef acc, const pg8::Unit& u, int wr, int wc, int fr, int fq) const {
;         const int row0 = u.pm * 256 + wr * 64 + fr, col = u.pn * 128 + wc * 32 + 8 * fq;
; #pragma unroll
;         for (int ai = 0; ai < 2; ++ai)
; #pragma unroll
;             for (int m = 0; m < 4; ++m) { bf16_t* rowp = Hm + (size_t)(row0 + ai * 128 + m * 16) * DFF + col; float h[8];
; #pragma unroll
;                 for (int j = 0; j < 8; ++j) { const float gt = acc[ai][0][m][j >> 2][j & 3], up = acc[ai][1][m][j >> 2][j & 3]; h[j] = gt * sigmoidf_(gt) * up; }
;                 u32x4 w; w.x = cvtpk(h[0], h[1]); w.y = cvtpk(h[2], h[3]); w.z = cvtpk(h[4], h[5]); w.w = cvtpk(h[6], h[7]);
;                 if (ai == 0 && m == 0) asm volatile("s_waitcnt vmcnt(0)" ::: "memory");
;                 __builtin_nontemporal_store(w, (u32x4*)rowp); }
	v_rcp_f32_e32 v125, v125
	flat_store_dwordx4 v[122:123], v[118:121]
	v_mul_f32_e32 v108, v108, v112
	v_mul_f32_e32 v112, 0xbfb8aa3b, v110
	v_mul_f32_e32 v118, 0xbfb8aa3b, v111
	v_exp_f32_e32 v112, v112
	v_exp_f32_e32 v118, v118
	v_mul_f32_e32 v109, v109, v125
	v_mul_f32_e32 v109, v109, v113
	v_add_f32_e32 v112, 1.0, v112
	v_add_f32_e32 v113, 1.0, v118
	v_mul_f32_e32 v118, 0xbfb8aa3b, v100
	v_rcp_f32_e32 v112, v112
	v_exp_f32_e32 v118, v118
	v_rcp_f32_e32 v113, v113
	s_mov_b64 s[22:23], -1
	v_mul_f32_e32 v110, v110, v112
	v_add_f32_e32 v112, 1.0, v118
	v_mul_f32_e32 v111, v111, v113
	v_rcp_f32_e32 v112, v112
	v_mul_f32_e32 v113, 0xbfb8aa3b, v101
	v_exp_f32_e32 v113, v113
	v_mul_f32_e32 v110, v110, v114
	v_mul_f32_e32 v100, v100, v112
	v_mul_f32_e32 v104, v100, v104
	v_add_f32_e32 v100, 1.0, v113
	v_mul_f32_e32 v112, 0xbfb8aa3b, v102
	v_rcp_f32_e32 v100, v100
	v_exp_f32_e32 v112, v112
	v_mul_f32_e32 v113, 0xbfb8aa3b, v103
	v_exp_f32_e32 v113, v113
	v_mul_f32_e32 v100, v101, v100
	v_add_f32_e32 v101, 1.0, v112
	v_rcp_f32_e32 v101, v101
	v_add_f32_e32 v112, 1.0, v113
	v_rcp_f32_e32 v112, v112
	v_mul_f32_e32 v105, v100, v105
	v_mul_f32_e32 v100, v102, v101
	v_mul_f32_e32 v106, v100, v106
	v_mul_f32_e32 v100, v103, v112
	v_mul_f32_e32 v103, v100, v107
	v_mul_f32_e32 v111, v111, v115
	v_cvt_pk_bf16_f32 v100, v108, v109
	v_cvt_pk_bf16_f32 v101, v110, v111
	v_cvt_pk_bf16_f32 v102, v104, v105
	v_cvt_pk_bf16_f32 v103, v106, v103
	v_mul_f32_e32 v106, 0xbfb8aa3b, v92
	v_exp_f32_e32 v106, v106
	v_mul_f32_e32 v107, 0xbfb8aa3b, v93
	v_exp_f32_e32 v107, v107
	v_or_b32_e32 v104, 16, v0
	v_add_f32_e32 v106, 1.0, v106
	v_rcp_f32_e32 v106, v106
	v_mad_i64_i32 v[104:105], s[18:19], v104, s3, v[2:3]
	v_lshl_add_u64 v[104:105], v[104:105], 0, v[116:117]
	v_add_f32_e32 v107, 1.0, v107
	v_mul_f32_e32 v92, v92, v106
	v_rcp_f32_e32 v107, v107
	flat_store_dwordx4 v[104:105], v[100:103]
	v_mul_f32_e32 v92, v92, v96
	v_mul_f32_e32 v96, 0xbfb8aa3b, v94
	v_mul_f32_e32 v100, 0xbfb8aa3b, v95
	v_exp_f32_e32 v96, v96
	v_exp_f32_e32 v100, v100
	v_mul_f32_e32 v93, v93, v107
	v_mul_f32_e32 v93, v93, v97
	v_add_f32_e32 v96, 1.0, v96
	v_add_f32_e32 v97, 1.0, v100
	v_mul_f32_e32 v100, 0xbfb8aa3b, v84
	v_rcp_f32_e32 v96, v96
	v_exp_f32_e32 v100, v100
	v_rcp_f32_e32 v97, v97
	s_and_b64 vcc, exec, s[4:5]
	v_mul_f32_e32 v94, v94, v96
	v_add_f32_e32 v96, 1.0, v100
	v_mul_f32_e32 v95, v95, v97
	v_rcp_f32_e32 v96, v96
	v_mul_f32_e32 v97, 0xbfb8aa3b, v85
	v_exp_f32_e32 v97, v97
	v_mul_f32_e32 v94, v94, v98
	v_mul_f32_e32 v84, v84, v96
	v_mul_f32_e32 v88, v84, v88
	v_add_f32_e32 v84, 1.0, v97
	v_mul_f32_e32 v96, 0xbfb8aa3b, v86
	v_rcp_f32_e32 v84, v84
	v_exp_f32_e32 v96, v96
	v_mul_f32_e32 v97, 0xbfb8aa3b, v87
	v_exp_f32_e32 v97, v97
	v_mul_f32_e32 v84, v85, v84
	v_add_f32_e32 v85, 1.0, v96
	v_rcp_f32_e32 v85, v85
	v_add_f32_e32 v96, 1.0, v97
	v_rcp_f32_e32 v96, v96
	v_mul_f32_e32 v89, v84, v89
	v_mul_f32_e32 v84, v86, v85
	v_mul_f32_e32 v90, v84, v90
	v_mul_f32_e32 v84, v87, v96
	v_mul_f32_e32 v87, v84, v91
	v_mul_f32_e32 v95, v95, v99
	v_cvt_pk_bf16_f32 v84, v92, v93
	v_cvt_pk_bf16_f32 v85, v94, v95
	v_cvt_pk_bf16_f32 v86, v88, v89
	v_cvt_pk_bf16_f32 v87, v90, v87
	v_mul_f32_e32 v90, 0xbfb8aa3b, v76
	v_exp_f32_e32 v90, v90
	v_mul_f32_e32 v91, 0xbfb8aa3b, v77
	v_exp_f32_e32 v91, v91
	v_or_b32_e32 v88, 32, v0
	v_add_f32_e32 v90, 1.0, v90
	v_rcp_f32_e32 v90, v90
	v_mad_i64_i32 v[88:89], s[18:19], v88, s3, v[2:3]
	v_lshl_add_u64 v[88:89], v[88:89], 0, v[116:117]
	v_add_f32_e32 v91, 1.0, v91
	v_mul_f32_e32 v76, v76, v90
	v_rcp_f32_e32 v91, v91
	flat_store_dwordx4 v[88:89], v[84:87]
	v_mul_f32_e32 v76, v76, v80
	v_mul_f32_e32 v80, 0xbfb8aa3b, v78
	v_mul_f32_e32 v84, 0xbfb8aa3b, v79
	v_exp_f32_e32 v80, v80
	v_exp_f32_e32 v84, v84
	v_mul_f32_e32 v77, v77, v91
	v_mul_f32_e32 v77, v77, v81
	v_add_f32_e32 v80, 1.0, v80
	v_add_f32_e32 v81, 1.0, v84
	v_mul_f32_e32 v84, 0xbfb8aa3b, v64
	v_rcp_f32_e32 v80, v80
	v_exp_f32_e32 v84, v84
	v_rcp_f32_e32 v81, v81
	s_mov_b32 s75, s6
	v_mul_f32_e32 v78, v78, v80
	v_add_f32_e32 v80, 1.0, v84
	v_mul_f32_e32 v79, v79, v81
	v_rcp_f32_e32 v80, v80
	v_mul_f32_e32 v81, 0xbfb8aa3b, v65
	v_exp_f32_e32 v81, v81
	v_mul_f32_e32 v78, v78, v82
	v_mul_f32_e32 v64, v64, v80
	v_mul_f32_e32 v72, v64, v72
	v_add_f32_e32 v64, 1.0, v81
	v_mul_f32_e32 v80, 0xbfb8aa3b, v66
	v_rcp_f32_e32 v64, v64
	v_exp_f32_e32 v80, v80
	v_mul_f32_e32 v81, 0xbfb8aa3b, v67
	v_exp_f32_e32 v81, v81
	v_mul_f32_e32 v64, v65, v64
	v_add_f32_e32 v65, 1.0, v80
	v_rcp_f32_e32 v65, v65
	v_add_f32_e32 v80, 1.0, v81
	v_rcp_f32_e32 v80, v80
	v_mul_f32_e32 v73, v64, v73
	v_mul_f32_e32 v64, v66, v65
	v_mul_f32_e32 v74, v64, v74
	v_mul_f32_e32 v64, v67, v80
	v_mul_f32_e32 v79, v79, v83
	v_mul_f32_e32 v67, v64, v75
	v_cvt_pk_bf16_f32 v64, v76, v77
	v_cvt_pk_bf16_f32 v65, v78, v79
	v_cvt_pk_bf16_f32 v66, v72, v73
	v_or_b32_e32 v72, 48, v0
	v_mad_i64_i32 v[72:73], s[18:19], v72, s3, v[2:3]
	v_lshl_add_u64 v[72:73], v[72:73], 0, v[116:117]
	v_cvt_pk_bf16_f32 v67, v74, v67
	flat_store_dwordx4 v[72:73], v[64:67]
	v_mul_f32_e32 v74, 0xbfb8aa3b, v60
	v_mul_f32_e32 v75, 0xbfb8aa3b, v61
	v_mul_f32_e32 v64, 0xbfb8aa3b, v62
	v_exp_f32_e32 v64, v64
	v_mul_f32_e32 v65, 0xbfb8aa3b, v63
	v_exp_f32_e32 v65, v65
	v_mul_f32_e32 v66, 0xbfb8aa3b, v52
	v_add_f32_e32 v64, 1.0, v64
	v_rcp_f32_e32 v64, v64
	v_add_f32_e32 v65, 1.0, v65
	v_exp_f32_e32 v66, v66
	v_rcp_f32_e32 v65, v65
	v_mul_f32_e32 v62, v62, v64
	v_exp_f32_e32 v74, v74
	v_add_f32_e32 v64, 1.0, v66
	v_mul_f32_e32 v63, v63, v65
	v_rcp_f32_e32 v64, v64
	v_mul_f32_e32 v65, 0xbfb8aa3b, v53
	v_exp_f32_e32 v65, v65
	v_exp_f32_e32 v75, v75
	v_mul_f32_e32 v52, v52, v64
; DEVI unsigned cvtpk(float lo, float hi) { unsigned r; asm volatile("v_cvt_pk_bf16_f32 %0, %1, %2" : "=v"(r) : "v"(lo), "v"(hi)); return r; }
; DEVI float sigmoidf_(float x) { return __builtin_amdgcn_rcpf(1.f + __expf(-x)); }
; #define PG8_WAIT_V(n) asm volatile("s_waitcnt vmcnt(" #n ")" ::: "memory")
; #define PG8_BAR __builtin_amdgcn_s_barrier()
; template <class Epi, class Sched>
; __device__ __forceinline__ void gemm_phase(PG8_LAS unsigned char* lds, const Gemm g, const Sched& S, const Epi& E, int wv) {
;     ...
;         cur = nxt; cA = nA; cB = nB; ++ui;
;     }
;     PG8_WAIT_V(0);
;     if (wr == 0) PG8_BAR;
;     PG8_BAR;
;     DEVI void operator()(AccRef acc, const pg8::Unit& u, int wr, int wc, int fr, int fq) const {
;         const int row0 = u.pm * 256 + wr * 64 + fr, col = u.pn * 128 + wc * 32 + 8 * fq;
; #pragma unroll
;         for (int ai = 0; ai < 2; ++ai)
; #pragma unroll
;             for (int m = 0; m < 4; ++m) { bf16_t* rowp = Hm + (size_t)(row0 + ai * 128 + m * 16) * DFF + col; float h[8];
; #pragma unroll
;                 for (int j = 0; j < 8; ++j) { const float gt = acc[ai][0][m][j >> 2][j & 3], up = acc[ai][1][m][j >> 2][j & 3]; h[j] = gt * sigmoidf_(gt) * up; }
;                 u32x4 w; w.x = cvtpk(h[0], h[1]); w.y = cvtpk(h[2], h[3]); w.z = cvtpk(h[4], h[5]); w.w = cvtpk(h[6], h[7]);
;                 if (ai == 0 && m == 0) asm volatile("s_waitcnt vmcnt(0)" ::: "memory");
;                 __builtin_nontemporal_store(w, (u32x4*)rowp); }
	v_mul_f32_e32 v56, v52, v56
	v_add_f32_e32 v52, 1.0, v65
	v_mul_f32_e32 v64, 0xbfb8aa3b, v54
	v_rcp_f32_e32 v52, v52
	v_exp_f32_e32 v64, v64
	v_mul_f32_e32 v65, 0xbfb8aa3b, v55
	v_exp_f32_e32 v65, v65
	v_mul_f32_e32 v52, v53, v52
	v_add_f32_e32 v53, 1.0, v64
	v_rcp_f32_e32 v53, v53
	v_add_f32_e32 v64, 1.0, v65
	v_add_f32_e32 v74, 1.0, v74
	v_add_f32_e32 v75, 1.0, v75
	v_rcp_f32_e32 v64, v64
	v_rcp_f32_e32 v74, v74
	v_rcp_f32_e32 v75, v75
	v_mul_f32_e32 v57, v52, v57
	v_mul_f32_e32 v52, v54, v53
	v_mul_f32_e32 v58, v52, v58
	v_mul_f32_e32 v52, v55, v64
	v_mul_f32_e32 v60, v60, v74
	v_mul_f32_e32 v61, v61, v75
	v_mul_f32_e32 v55, v52, v59
	v_mul_f32_e32 v60, v60, v68
	v_mul_f32_e32 v61, v61, v69
	v_mul_f32_e32 v62, v62, v70
	v_mul_f32_e32 v63, v63, v71
	v_cvt_pk_bf16_f32 v52, v60, v61
	v_cvt_pk_bf16_f32 v53, v62, v63
	v_cvt_pk_bf16_f32 v54, v56, v57
	v_cvt_pk_bf16_f32 v55, v58, v55
	v_mul_f32_e32 v58, 0xbfb8aa3b, v44
	v_exp_f32_e32 v58, v58
	v_mul_f32_e32 v59, 0xbfb8aa3b, v45
	v_exp_f32_e32 v59, v59
	v_add_u32_e32 v56, 0x80, v0
	v_add_f32_e32 v58, 1.0, v58
	v_rcp_f32_e32 v58, v58
	v_mad_i64_i32 v[56:57], s[18:19], v56, s3, v[2:3]
	v_lshl_add_u64 v[56:57], v[56:57], 0, v[116:117]
	v_add_f32_e32 v59, 1.0, v59
	v_mul_f32_e32 v44, v44, v58
	v_rcp_f32_e32 v59, v59
	flat_store_dwordx4 v[56:57], v[52:55]
	v_mul_f32_e32 v44, v44, v48
	v_mul_f32_e32 v48, 0xbfb8aa3b, v46
	v_mul_f32_e32 v52, 0xbfb8aa3b, v47
	v_exp_f32_e32 v48, v48
	v_exp_f32_e32 v52, v52
	v_mul_f32_e32 v45, v45, v59
	v_mul_f32_e32 v45, v45, v49
	v_add_f32_e32 v48, 1.0, v48
	v_add_f32_e32 v49, 1.0, v52
	v_mul_f32_e32 v52, 0xbfb8aa3b, v36
	v_rcp_f32_e32 v48, v48
	v_exp_f32_e32 v52, v52
	v_rcp_f32_e32 v49, v49
	s_mov_b32 s10, s8
	v_mul_f32_e32 v46, v46, v48
	v_add_f32_e32 v48, 1.0, v52
	v_mul_f32_e32 v47, v47, v49
	v_rcp_f32_e32 v48, v48
	v_mul_f32_e32 v49, 0xbfb8aa3b, v37
	v_exp_f32_e32 v49, v49
	v_mul_f32_e32 v46, v46, v50
	v_mul_f32_e32 v36, v36, v48
	v_mul_f32_e32 v40, v36, v40
	v_add_f32_e32 v36, 1.0, v49
	v_mul_f32_e32 v48, 0xbfb8aa3b, v38
	v_rcp_f32_e32 v36, v36
	v_exp_f32_e32 v48, v48
	v_mul_f32_e32 v49, 0xbfb8aa3b, v39
	v_exp_f32_e32 v49, v49
	v_mul_f32_e32 v36, v37, v36
	v_add_f32_e32 v37, 1.0, v48
	v_rcp_f32_e32 v37, v37
	v_add_f32_e32 v48, 1.0, v49
	v_rcp_f32_e32 v48, v48
	v_mul_f32_e32 v41, v36, v41
	v_mul_f32_e32 v36, v38, v37
	v_mul_f32_e32 v42, v36, v42
	v_mul_f32_e32 v36, v39, v48
	v_mul_f32_e32 v39, v36, v43
	v_mul_f32_e32 v47, v47, v51
	v_cvt_pk_bf16_f32 v36, v44, v45
	v_cvt_pk_bf16_f32 v37, v46, v47
	v_cvt_pk_bf16_f32 v38, v40, v41
	v_cvt_pk_bf16_f32 v39, v42, v39
	v_mul_f32_e32 v42, 0xbfb8aa3b, v28
	v_exp_f32_e32 v42, v42
	v_mul_f32_e32 v43, 0xbfb8aa3b, v29
	v_exp_f32_e32 v43, v43
	v_add_u32_e32 v40, 0x90, v0
	v_add_f32_e32 v42, 1.0, v42
	v_rcp_f32_e32 v42, v42
	v_mad_i64_i32 v[40:41], s[18:19], v40, s3, v[2:3]
	v_lshl_add_u64 v[40:41], v[40:41], 0, v[116:117]
	v_add_f32_e32 v43, 1.0, v43
	v_mul_f32_e32 v28, v28, v42
	v_rcp_f32_e32 v43, v43
	flat_store_dwordx4 v[40:41], v[36:39]
	v_mul_f32_e32 v28, v28, v32
	v_mul_f32_e32 v32, 0xbfb8aa3b, v30
	v_mul_f32_e32 v36, 0xbfb8aa3b, v31
	v_exp_f32_e32 v32, v32
	v_exp_f32_e32 v36, v36
	v_mul_f32_e32 v29, v29, v43
	v_mul_f32_e32 v29, v29, v33
	v_add_f32_e32 v32, 1.0, v32
	v_add_f32_e32 v33, 1.0, v36
	v_mul_f32_e32 v36, 0xbfb8aa3b, v20
	v_rcp_f32_e32 v32, v32
	v_exp_f32_e32 v36, v36
	v_rcp_f32_e32 v33, v33
	s_mov_b64 s[20:21], s[12:13]
	v_mul_f32_e32 v30, v30, v32
	v_add_f32_e32 v32, 1.0, v36
	v_mul_f32_e32 v31, v31, v33
	v_rcp_f32_e32 v32, v32
	v_mul_f32_e32 v33, 0xbfb8aa3b, v21
	v_exp_f32_e32 v33, v33
	v_mul_f32_e32 v30, v30, v34
	v_mul_f32_e32 v20, v20, v32
	v_mul_f32_e32 v24, v20, v24
	v_add_f32_e32 v20, 1.0, v33
	v_mul_f32_e32 v32, 0xbfb8aa3b, v22
	v_rcp_f32_e32 v20, v20
	v_exp_f32_e32 v32, v32
	v_mul_f32_e32 v33, 0xbfb8aa3b, v23
	v_exp_f32_e32 v33, v33
	v_mul_f32_e32 v20, v21, v20
	v_add_f32_e32 v21, 1.0, v32
	v_rcp_f32_e32 v21, v21
	v_add_f32_e32 v32, 1.0, v33
	v_rcp_f32_e32 v32, v32
	v_mul_f32_e32 v25, v20, v25
	v_mul_f32_e32 v20, v22, v21
	v_mul_f32_e32 v26, v20, v26
	v_mul_f32_e32 v20, v23, v32
	v_mul_f32_e32 v23, v20, v27
	v_mul_f32_e32 v31, v31, v35
	v_cvt_pk_bf16_f32 v20, v28, v29
	v_cvt_pk_bf16_f32 v21, v30, v31
	v_cvt_pk_bf16_f32 v22, v24, v25
	v_cvt_pk_bf16_f32 v23, v26, v23
	v_mul_f32_e32 v26, 0xbfb8aa3b, v12
	v_exp_f32_e32 v26, v26
	v_mul_f32_e32 v27, 0xbfb8aa3b, v13
	v_exp_f32_e32 v27, v27
	v_add_u32_e32 v24, 0xa0, v0
	v_add_f32_e32 v26, 1.0, v26
	v_rcp_f32_e32 v26, v26
	v_mad_i64_i32 v[24:25], s[18:19], v24, s3, v[2:3]
	v_lshl_add_u64 v[24:25], v[24:25], 0, v[116:117]
	v_add_f32_e32 v27, 1.0, v27
	v_mul_f32_e32 v12, v12, v26
	v_rcp_f32_e32 v27, v27
	flat_store_dwordx4 v[24:25], v[20:23]
	v_mul_f32_e32 v12, v12, v16
	v_mul_f32_e32 v16, 0xbfb8aa3b, v14
	v_mul_f32_e32 v20, 0xbfb8aa3b, v15
	v_exp_f32_e32 v16, v16
	v_exp_f32_e32 v20, v20
	v_mul_f32_e32 v13, v13, v27
	v_mul_f32_e32 v13, v13, v17
	v_add_f32_e32 v16, 1.0, v16
	v_add_f32_e32 v17, 1.0, v20
	v_mul_f32_e32 v20, 0xbfb8aa3b, v4
	v_rcp_f32_e32 v16, v16
	v_exp_f32_e32 v20, v20
	v_rcp_f32_e32 v17, v17
	v_add_u32_e32 v0, 0xb0, v0
	v_mul_f32_e32 v14, v14, v16
	v_add_f32_e32 v16, 1.0, v20
	v_mul_f32_e32 v15, v15, v17
	v_rcp_f32_e32 v16, v16
	v_mul_f32_e32 v17, 0xbfb8aa3b, v5
	v_exp_f32_e32 v17, v17
	v_mad_i64_i32 v[2:3], s[18:19], v0, s3, v[2:3]
	v_mul_f32_e32 v4, v4, v16
	v_mul_f32_e32 v8, v4, v8
	v_add_f32_e32 v4, 1.0, v17
	v_mul_f32_e32 v16, 0xbfb8aa3b, v6
	v_rcp_f32_e32 v4, v4
	v_exp_f32_e32 v16, v16
	v_mul_f32_e32 v17, 0xbfb8aa3b, v7
	v_exp_f32_e32 v17, v17
	v_mul_f32_e32 v4, v5, v4
	v_add_f32_e32 v5, 1.0, v16
	v_rcp_f32_e32 v5, v5
	v_add_f32_e32 v16, 1.0, v17
	v_rcp_f32_e32 v16, v16
	v_mul_f32_e32 v9, v4, v9
	v_mul_f32_e32 v4, v6, v5
	v_mul_f32_e32 v10, v4, v10
	v_mul_f32_e32 v4, v7, v16
	v_mul_f32_e32 v7, v4, v11
	v_lshl_add_u64 v[2:3], v[2:3], 0, v[116:117]
	s_mov_b64 s[18:19], s[14:15]
	v_mul_f32_e32 v14, v14, v18
	v_mul_f32_e32 v15, v15, v19
	v_cvt_pk_bf16_f32 v4, v12, v13
	v_cvt_pk_bf16_f32 v5, v14, v15
	v_cvt_pk_bf16_f32 v6, v8, v9
	v_cvt_pk_bf16_f32 v7, v10, v7
	flat_store_dwordx4 v[2:3], v[4:7]
	s_cbranch_vccz .LBB0_522
	s_waitcnt vmcnt(0)
	s_cmpk_gt_u32 s24, 0xff
	s_cbranch_scc1 .LBB0_532
	s_barrier
